# r2 cross-chunk MFMA section: LDS fragment reads software-pipelined 6 deep ahead of the MFMAs instead of read-wait-MFMA
# baseline (speedup 1.0000x reference)
.LBB0_71:
	s_waitcnt lgkmcnt(0)
	s_barrier
	ds_read_b128 v[82:85], v197
	ds_read_b128 v[86:89], v197 offset:64
	ds_read_b128 v[90:93], v197 offset:128
	ds_read_b128 v[94:97], v197 offset:192
	ds_read_b128 v[98:101], v197 offset:4352
	ds_read_b128 v[102:105], v197 offset:4416
	v_cndmask_b32_e64 v80, v200, v201, s[8:9]
	v_readlane_b32 s40, v254, 59
	v_readlane_b32 s41, v254, 60
	s_mov_b64 s[22:23], s[44:45]
	s_waitcnt lgkmcnt(5)
	v_mfma_f32_16x16x32_bf16 v[106:109], v[82:85], v[0:3], 0
	ds_read_b128 v[82:85], v197 offset:4480
	s_waitcnt lgkmcnt(5)
	v_mfma_f32_16x16x32_bf16 v[106:109], v[86:89], v[4:7], v[106:109]
	ds_read_b128 v[86:89], v197 offset:4544
	s_waitcnt lgkmcnt(5)
	v_mfma_f32_16x16x32_bf16 v[106:109], v[90:93], v[8:11], v[106:109]
	ds_read_b128 v[90:93], v197 offset:8704
	s_waitcnt lgkmcnt(5)
	v_mfma_f32_16x16x32_bf16 v[106:109], v[94:97], v[12:15], v[106:109]
	ds_read_b128 v[94:97], v197 offset:8768
	s_nop 6
	v_pk_fma_f32 v[16:17], v[80:81], v[106:107], v[16:17] op_sel_hi:[0,1,1]
	v_pk_fma_f32 v[18:19], v[80:81], v[108:109], v[18:19] op_sel_hi:[0,1,1]
	s_waitcnt lgkmcnt(5)
	v_mfma_f32_16x16x32_bf16 v[106:109], v[98:101], v[0:3], 0
	ds_read_b128 v[98:101], v197 offset:8832
	s_waitcnt lgkmcnt(5)
	v_mfma_f32_16x16x32_bf16 v[106:109], v[102:105], v[4:7], v[106:109]
	ds_read_b128 v[102:105], v197 offset:8896
	s_waitcnt lgkmcnt(5)
	v_mfma_f32_16x16x32_bf16 v[106:109], v[82:85], v[8:11], v[106:109]
	ds_read_b128 v[82:85], v197 offset:13056
	s_waitcnt lgkmcnt(5)
	v_mfma_f32_16x16x32_bf16 v[106:109], v[86:89], v[12:15], v[106:109]
	ds_read_b128 v[86:89], v197 offset:13120
	s_nop 6
	v_pk_fma_f32 v[20:21], v[80:81], v[106:107], v[20:21] op_sel_hi:[0,1,1]
	v_pk_fma_f32 v[22:23], v[80:81], v[108:109], v[22:23] op_sel_hi:[0,1,1]
	s_waitcnt lgkmcnt(5)
	v_mfma_f32_16x16x32_bf16 v[106:109], v[90:93], v[0:3], 0
	ds_read_b128 v[90:93], v197 offset:13184
	s_waitcnt lgkmcnt(5)
	v_mfma_f32_16x16x32_bf16 v[106:109], v[94:97], v[4:7], v[106:109]
	ds_read_b128 v[94:97], v197 offset:13248
	s_waitcnt lgkmcnt(5)
	v_mfma_f32_16x16x32_bf16 v[106:109], v[98:101], v[8:11], v[106:109]
	ds_read_b128 v[98:101], v197 offset:17408
	s_waitcnt lgkmcnt(5)
	v_mfma_f32_16x16x32_bf16 v[106:109], v[102:105], v[12:15], v[106:109]
	ds_read_b128 v[102:105], v197 offset:17472
	s_nop 6
	v_pk_fma_f32 v[24:25], v[80:81], v[106:107], v[24:25] op_sel_hi:[0,1,1]
	v_pk_fma_f32 v[26:27], v[80:81], v[108:109], v[26:27] op_sel_hi:[0,1,1]
	s_waitcnt lgkmcnt(5)
	v_mfma_f32_16x16x32_bf16 v[106:109], v[82:85], v[0:3], 0
	ds_read_b128 v[82:85], v197 offset:17536
	s_waitcnt lgkmcnt(5)
	v_mfma_f32_16x16x32_bf16 v[106:109], v[86:89], v[4:7], v[106:109]
	ds_read_b128 v[86:89], v197 offset:17600
	s_waitcnt lgkmcnt(5)
	v_mfma_f32_16x16x32_bf16 v[106:109], v[90:93], v[8:11], v[106:109]
	ds_read_b128 v[90:93], v197 offset:21760
	s_waitcnt lgkmcnt(5)
	v_mfma_f32_16x16x32_bf16 v[106:109], v[94:97], v[12:15], v[106:109]
	ds_read_b128 v[94:97], v197 offset:21824
	s_nop 6
	v_pk_fma_f32 v[28:29], v[80:81], v[106:107], v[28:29] op_sel_hi:[0,1,1]
	v_pk_fma_f32 v[30:31], v[80:81], v[108:109], v[30:31] op_sel_hi:[0,1,1]
	s_waitcnt lgkmcnt(5)
	v_mfma_f32_16x16x32_bf16 v[106:109], v[98:101], v[0:3], 0
	ds_read_b128 v[98:101], v197 offset:21888
	s_waitcnt lgkmcnt(5)
	v_mfma_f32_16x16x32_bf16 v[106:109], v[102:105], v[4:7], v[106:109]
	ds_read_b128 v[102:105], v197 offset:21952
	s_waitcnt lgkmcnt(5)
	v_mfma_f32_16x16x32_bf16 v[106:109], v[82:85], v[8:11], v[106:109]
	ds_read_b128 v[82:85], v197 offset:26112
	s_waitcnt lgkmcnt(5)
	v_mfma_f32_16x16x32_bf16 v[106:109], v[86:89], v[12:15], v[106:109]
	ds_read_b128 v[86:89], v197 offset:26176
	s_nop 6
	v_pk_fma_f32 v[32:33], v[80:81], v[106:107], v[32:33] op_sel_hi:[0,1,1]
	v_pk_fma_f32 v[34:35], v[80:81], v[108:109], v[34:35] op_sel_hi:[0,1,1]
	s_waitcnt lgkmcnt(5)
	v_mfma_f32_16x16x32_bf16 v[106:109], v[90:93], v[0:3], 0
	ds_read_b128 v[90:93], v197 offset:26240
	s_waitcnt lgkmcnt(5)
	v_mfma_f32_16x16x32_bf16 v[106:109], v[94:97], v[4:7], v[106:109]
	ds_read_b128 v[94:97], v197 offset:26304
	s_waitcnt lgkmcnt(5)
	v_mfma_f32_16x16x32_bf16 v[106:109], v[98:101], v[8:11], v[106:109]
	ds_read_b128 v[98:101], v197 offset:30464
	s_waitcnt lgkmcnt(5)
	v_mfma_f32_16x16x32_bf16 v[106:109], v[102:105], v[12:15], v[106:109]
	ds_read_b128 v[102:105], v197 offset:30528
	s_nop 6
	v_pk_fma_f32 v[36:37], v[80:81], v[106:107], v[36:37] op_sel_hi:[0,1,1]
	v_pk_fma_f32 v[38:39], v[80:81], v[108:109], v[38:39] op_sel_hi:[0,1,1]
	s_waitcnt lgkmcnt(5)
	v_mfma_f32_16x16x32_bf16 v[106:109], v[82:85], v[0:3], 0
	ds_read_b128 v[82:85], v197 offset:30592
	s_waitcnt lgkmcnt(5)
	v_mfma_f32_16x16x32_bf16 v[106:109], v[86:89], v[4:7], v[106:109]
	ds_read_b128 v[86:89], v197 offset:30656
	s_waitcnt lgkmcnt(5)
	v_mfma_f32_16x16x32_bf16 v[106:109], v[90:93], v[8:11], v[106:109]
	ds_read_b128 v[90:93], v197 offset:34816
	s_waitcnt lgkmcnt(5)
	v_mfma_f32_16x16x32_bf16 v[106:109], v[94:97], v[12:15], v[106:109]
	ds_read_b128 v[94:97], v197 offset:34880
	s_nop 6
	v_pk_fma_f32 v[40:41], v[80:81], v[106:107], v[40:41] op_sel_hi:[0,1,1]
	v_pk_fma_f32 v[42:43], v[80:81], v[108:109], v[42:43] op_sel_hi:[0,1,1]
	s_waitcnt lgkmcnt(5)
	v_mfma_f32_16x16x32_bf16 v[106:109], v[98:101], v[0:3], 0
	ds_read_b128 v[98:101], v197 offset:34944
	s_waitcnt lgkmcnt(5)
	v_mfma_f32_16x16x32_bf16 v[106:109], v[102:105], v[4:7], v[106:109]
	ds_read_b128 v[102:105], v197 offset:35008
	s_waitcnt lgkmcnt(5)
	v_mfma_f32_16x16x32_bf16 v[106:109], v[82:85], v[8:11], v[106:109]
	ds_read_b128 v[82:85], v197 offset:39168
	s_waitcnt lgkmcnt(5)
	v_mfma_f32_16x16x32_bf16 v[106:109], v[86:89], v[12:15], v[106:109]
	ds_read_b128 v[86:89], v197 offset:39232
	s_nop 6
	v_pk_fma_f32 v[44:45], v[80:81], v[106:107], v[44:45] op_sel_hi:[0,1,1]
	v_pk_fma_f32 v[46:47], v[80:81], v[108:109], v[46:47] op_sel_hi:[0,1,1]
	s_waitcnt lgkmcnt(5)
	v_mfma_f32_16x16x32_bf16 v[106:109], v[90:93], v[0:3], 0
	ds_read_b128 v[90:93], v197 offset:39296
	s_waitcnt lgkmcnt(5)
	v_mfma_f32_16x16x32_bf16 v[106:109], v[94:97], v[4:7], v[106:109]
	ds_read_b128 v[94:97], v197 offset:39360
	s_waitcnt lgkmcnt(5)
	v_mfma_f32_16x16x32_bf16 v[106:109], v[98:101], v[8:11], v[106:109]
	ds_read_b128 v[98:101], v197 offset:43520
	s_waitcnt lgkmcnt(5)
	v_mfma_f32_16x16x32_bf16 v[106:109], v[102:105], v[12:15], v[106:109]
	ds_read_b128 v[102:105], v197 offset:43584
	s_nop 6
	v_pk_fma_f32 v[48:49], v[80:81], v[106:107], v[48:49] op_sel_hi:[0,1,1]
	v_pk_fma_f32 v[50:51], v[80:81], v[108:109], v[50:51] op_sel_hi:[0,1,1]
	s_waitcnt lgkmcnt(5)
	v_mfma_f32_16x16x32_bf16 v[106:109], v[82:85], v[0:3], 0
	ds_read_b128 v[82:85], v197 offset:43648
	s_waitcnt lgkmcnt(5)
	v_mfma_f32_16x16x32_bf16 v[106:109], v[86:89], v[4:7], v[106:109]
	ds_read_b128 v[86:89], v197 offset:43712
	s_waitcnt lgkmcnt(5)
	v_mfma_f32_16x16x32_bf16 v[106:109], v[90:93], v[8:11], v[106:109]
	ds_read_b128 v[90:93], v197 offset:47872
	s_waitcnt lgkmcnt(5)
	v_mfma_f32_16x16x32_bf16 v[106:109], v[94:97], v[12:15], v[106:109]
	ds_read_b128 v[94:97], v197 offset:47936
	s_nop 6
	v_pk_fma_f32 v[52:53], v[80:81], v[106:107], v[52:53] op_sel_hi:[0,1,1]
	v_pk_fma_f32 v[54:55], v[80:81], v[108:109], v[54:55] op_sel_hi:[0,1,1]
	s_waitcnt lgkmcnt(5)
	v_mfma_f32_16x16x32_bf16 v[106:109], v[98:101], v[0:3], 0
	ds_read_b128 v[98:101], v197 offset:48000
	s_waitcnt lgkmcnt(5)
	v_mfma_f32_16x16x32_bf16 v[106:109], v[102:105], v[4:7], v[106:109]
	ds_read_b128 v[102:105], v197 offset:48064
	s_waitcnt lgkmcnt(5)
	v_mfma_f32_16x16x32_bf16 v[106:109], v[82:85], v[8:11], v[106:109]
	ds_read_b128 v[82:85], v197 offset:52224
	s_waitcnt lgkmcnt(5)
	v_mfma_f32_16x16x32_bf16 v[106:109], v[86:89], v[12:15], v[106:109]
	ds_read_b128 v[86:89], v197 offset:52288
	s_nop 6
	v_pk_fma_f32 v[56:57], v[80:81], v[106:107], v[56:57] op_sel_hi:[0,1,1]
	v_pk_fma_f32 v[58:59], v[80:81], v[108:109], v[58:59] op_sel_hi:[0,1,1]
	s_waitcnt lgkmcnt(5)
	v_mfma_f32_16x16x32_bf16 v[106:109], v[90:93], v[0:3], 0
	ds_read_b128 v[90:93], v197 offset:52352
	s_waitcnt lgkmcnt(5)
	v_mfma_f32_16x16x32_bf16 v[106:109], v[94:97], v[4:7], v[106:109]
	ds_read_b128 v[94:97], v197 offset:52416
	s_waitcnt lgkmcnt(5)
	v_mfma_f32_16x16x32_bf16 v[106:109], v[98:101], v[8:11], v[106:109]
	ds_read_b128 v[98:101], v197 offset:56576
	s_waitcnt lgkmcnt(5)
	v_mfma_f32_16x16x32_bf16 v[106:109], v[102:105], v[12:15], v[106:109]
	ds_read_b128 v[102:105], v197 offset:56640
	s_nop 6
	v_pk_fma_f32 v[60:61], v[80:81], v[106:107], v[60:61] op_sel_hi:[0,1,1]
	v_pk_fma_f32 v[62:63], v[80:81], v[108:109], v[62:63] op_sel_hi:[0,1,1]
	s_waitcnt lgkmcnt(5)
	v_mfma_f32_16x16x32_bf16 v[106:109], v[82:85], v[0:3], 0
	ds_read_b128 v[82:85], v197 offset:56704
	s_waitcnt lgkmcnt(5)
	v_mfma_f32_16x16x32_bf16 v[106:109], v[86:89], v[4:7], v[106:109]
	ds_read_b128 v[86:89], v197 offset:56768
	s_waitcnt lgkmcnt(5)
	v_mfma_f32_16x16x32_bf16 v[106:109], v[90:93], v[8:11], v[106:109]
	ds_read_b128 v[90:93], v197 offset:60928
	s_waitcnt lgkmcnt(5)
	v_mfma_f32_16x16x32_bf16 v[106:109], v[94:97], v[12:15], v[106:109]
	ds_read_b128 v[94:97], v197 offset:60992
	s_nop 6
	v_pk_fma_f32 v[64:65], v[80:81], v[106:107], v[64:65] op_sel_hi:[0,1,1]
	v_pk_fma_f32 v[66:67], v[80:81], v[108:109], v[66:67] op_sel_hi:[0,1,1]
	s_waitcnt lgkmcnt(5)
	v_mfma_f32_16x16x32_bf16 v[106:109], v[98:101], v[0:3], 0
	ds_read_b128 v[98:101], v197 offset:61056
	s_waitcnt lgkmcnt(5)
	v_mfma_f32_16x16x32_bf16 v[106:109], v[102:105], v[4:7], v[106:109]
	ds_read_b128 v[102:105], v197 offset:61120
	s_waitcnt lgkmcnt(5)
	v_mfma_f32_16x16x32_bf16 v[106:109], v[82:85], v[8:11], v[106:109]
	ds_read_b128 v[82:85], v197 offset:65280
	s_waitcnt lgkmcnt(5)
	v_mfma_f32_16x16x32_bf16 v[106:109], v[86:89], v[12:15], v[106:109]
	ds_read_b128 v[86:89], v197 offset:65344
	s_nop 6
	v_pk_fma_f32 v[68:69], v[80:81], v[106:107], v[68:69] op_sel_hi:[0,1,1]
	v_pk_fma_f32 v[70:71], v[80:81], v[108:109], v[70:71] op_sel_hi:[0,1,1]
	s_waitcnt lgkmcnt(5)
	v_mfma_f32_16x16x32_bf16 v[106:109], v[90:93], v[0:3], 0
	ds_read_b128 v[90:93], v197 offset:65408
	s_waitcnt lgkmcnt(5)
	v_mfma_f32_16x16x32_bf16 v[106:109], v[94:97], v[4:7], v[106:109]
	ds_read_b128 v[94:97], v197 offset:65472
	s_waitcnt lgkmcnt(5)
	v_mfma_f32_16x16x32_bf16 v[106:109], v[98:101], v[8:11], v[106:109]
	s_waitcnt lgkmcnt(4)
	v_mfma_f32_16x16x32_bf16 v[106:109], v[102:105], v[12:15], v[106:109]
	s_nop 7
	v_pk_fma_f32 v[72:73], v[80:81], v[106:107], v[72:73] op_sel_hi:[0,1,1]
	v_pk_fma_f32 v[74:75], v[80:81], v[108:109], v[74:75] op_sel_hi:[0,1,1]
	s_waitcnt lgkmcnt(3)
	v_mfma_f32_16x16x32_bf16 v[106:109], v[82:85], v[0:3], 0
	s_waitcnt lgkmcnt(2)
	v_mfma_f32_16x16x32_bf16 v[106:109], v[86:89], v[4:7], v[106:109]
	s_waitcnt lgkmcnt(1)
	v_mfma_f32_16x16x32_bf16 v[106:109], v[90:93], v[8:11], v[106:109]
	s_waitcnt lgkmcnt(0)
	v_mfma_f32_16x16x32_bf16 v[106:109], v[94:97], v[12:15], v[106:109]
	s_nop 7
	v_pk_fma_f32 v[76:77], v[80:81], v[106:107], v[76:77] op_sel_hi:[0,1,1]
	v_pk_fma_f32 v[78:79], v[80:81], v[108:109], v[78:79] op_sel_hi:[0,1,1]
